# v11 + grid barrier: waiting workgroups poll the top-level generation word directly (no per-XCD relay hop)
# speedup vs baseline: 1.0033x; 1.0033x over previous
.LBB0_86:
	s_lshl_b32 s0, s33, 8
	s_add_u32 s23, s36, s0
	s_addc_u32 s22, s37, 0
	v_mov_b32_e32 v1, s23
	v_add_co_u32_e32 v4, vcc, 0x1000, v1
	v_mov_b32_e32 v1, s22
	s_nop 0
	v_addc_co_u32_e32 v5, vcc, 0, v1, vcc
	v_mov_b32_e32 v1, 1
	flat_atomic_add v1, v[4:5], v1 offset:1024 sc0
	v_cvt_f32_u32_e32 v3, v2
	v_sub_u32_e32 v4, 0, v2
	v_rcp_iflag_f32_e32 v3, v3
	s_nop 0
	v_mul_f32_e32 v3, 0x4f7ffffe, v3
	v_cvt_u32_f32_e32 v3, v3
	v_mul_lo_u32 v4, v4, v3
	v_mul_hi_u32 v4, v3, v4
	v_add_u32_e32 v3, v3, v4
	s_waitcnt vmcnt(0) lgkmcnt(0)
	v_mul_hi_u32 v3, v1, v3
	v_mul_lo_u32 v5, v3, v2
	v_add_u32_e32 v4, 1, v1
	v_sub_u32_e32 v1, v1, v5
	v_add_u32_e32 v6, 1, v3
	v_cmp_ge_u32_e32 vcc, v1, v2
	v_sub_u32_e32 v5, v1, v2
	s_nop 0
	v_cndmask_b32_e32 v3, v3, v6, vcc
	v_cndmask_b32_e32 v1, v1, v5, vcc
	v_add_u32_e32 v5, 1, v3
	v_cmp_ge_u32_e32 vcc, v1, v2
	s_nop 1
	v_cndmask_b32_e32 v1, v3, v5, vcc
	v_mad_u64_u32 v[2:3], s[0:1], v2, v1, v[2:3]
	v_cmp_ne_u32_e32 vcc, v4, v2
	s_and_saveexec_b64 s[0:1], vcc
	s_xor_b64 s[0:1], exec, s[0:1]
	s_cbranch_execz .LBB0_99
	v_mov_b32_e32 v0, s36
	v_add_co_u32_e32 v2, vcc, 0x3000, v0
	v_mov_b32_e32 v0, s37
	s_nop 0
	v_addc_co_u32_e32 v3, vcc, 0, v0, vcc
	flat_load_dword v0, v[2:3] offset:1280 sc1
	s_add_u32 s6, s36, 0x3500
	s_addc_u32 s7, s37, 0
	s_waitcnt vmcnt(0) lgkmcnt(0)
	v_cmp_eq_u32_e32 vcc, v0, v1
	s_and_saveexec_b64 s[4:5], vcc
	s_cbranch_execz .LBB0_98
	s_mov_b32 s24, 1
	s_mov_b64 s[8:9], 0
	s_branch .LBB0_90

.LBB0_237:
	v_readlane_b32 s4, v255, 5
	s_lshl_b32 s4, s4, 2
	s_add_u32 s19, s22, s4
	s_addc_u32 s17, s23, 0
	v_mov_b32_e32 v1, s19
	v_add_co_u32_e32 v4, vcc, 0x1000, v1
	v_mov_b32_e32 v1, s17
	s_nop 0
	v_addc_co_u32_e32 v5, vcc, 0, v1, vcc
	flat_atomic_add v3, v[4:5], v230 offset:1024 sc0
	v_cvt_f32_u32_e32 v1, v2
	v_sub_u32_e32 v4, 0, v2
	v_rcp_iflag_f32_e32 v1, v1
	s_nop 0
	v_mul_f32_e32 v1, 0x4f7ffffe, v1
	v_cvt_u32_f32_e32 v1, v1
	v_mul_lo_u32 v4, v4, v1
	v_mul_hi_u32 v4, v1, v4
	v_add_u32_e32 v1, v1, v4
	s_waitcnt vmcnt(0) lgkmcnt(0)
	v_mul_hi_u32 v1, v3, v1
	v_mul_lo_u32 v4, v1, v2
	v_sub_u32_e32 v4, v3, v4
	v_cmp_ge_u32_e32 vcc, v4, v2
	v_add_u32_e32 v5, 1, v1
	s_nop 0
	v_cndmask_b32_e32 v1, v1, v5, vcc
	v_sub_u32_e32 v5, v4, v2
	v_cndmask_b32_e32 v4, v4, v5, vcc
	v_cmp_ge_u32_e32 vcc, v4, v2
	v_add_u32_e32 v4, 1, v1
	s_nop 0
	v_cndmask_b32_e32 v1, v1, v4, vcc
	v_add_u32_e32 v4, 1, v3
	v_mad_u64_u32 v[2:3], s[4:5], v2, v1, v[2:3]
	v_cmp_ne_u32_e32 vcc, v4, v2
	s_and_saveexec_b64 s[4:5], vcc
	s_xor_b64 s[4:5], exec, s[4:5]
	s_cbranch_execz .LBB0_250
	v_mov_b32_e32 v0, s22
	v_add_co_u32_e32 v2, vcc, 0x3000, v0
	v_mov_b32_e32 v0, s23
	s_nop 0
	v_addc_co_u32_e32 v3, vcc, 0, v0, vcc
	flat_load_dword v0, v[2:3] offset:1280 sc1
	s_add_u32 s26, s22, 0x3500
	s_addc_u32 s27, s23, 0
	s_waitcnt vmcnt(0) lgkmcnt(0)
	v_cmp_eq_u32_e32 vcc, v0, v1
	s_and_saveexec_b64 s[24:25], vcc
	s_cbranch_execz .LBB0_249
	s_mov_b32 s44, 1
	s_mov_b64 s[28:29], 0
	s_branch .LBB0_241

.LBB0_515:
	v_readlane_b32 s4, v255, 5
	s_lshl_b32 s4, s4, 2
	s_add_u32 s18, s20, s4
	s_addc_u32 s17, s21, 0
	v_mov_b32_e32 v1, s18
	v_add_co_u32_e32 v4, vcc, 0x1000, v1
	v_mov_b32_e32 v1, s17
	s_nop 0
	v_addc_co_u32_e32 v5, vcc, 0, v1, vcc
	flat_atomic_add v3, v[4:5], v230 offset:1024 sc0
	v_cvt_f32_u32_e32 v1, v2
	v_sub_u32_e32 v4, 0, v2
	v_rcp_iflag_f32_e32 v1, v1
	s_nop 0
	v_mul_f32_e32 v1, 0x4f7ffffe, v1
	v_cvt_u32_f32_e32 v1, v1
	v_mul_lo_u32 v4, v4, v1
	v_mul_hi_u32 v4, v1, v4
	v_add_u32_e32 v1, v1, v4
	s_waitcnt vmcnt(0) lgkmcnt(0)
	v_mul_hi_u32 v1, v3, v1
	v_mul_lo_u32 v4, v1, v2
	v_sub_u32_e32 v4, v3, v4
	v_cmp_ge_u32_e32 vcc, v4, v2
	v_add_u32_e32 v5, 1, v1
	s_nop 0
	v_cndmask_b32_e32 v1, v1, v5, vcc
	v_sub_u32_e32 v5, v4, v2
	v_cndmask_b32_e32 v4, v4, v5, vcc
	v_cmp_ge_u32_e32 vcc, v4, v2
	v_add_u32_e32 v4, 1, v1
	s_nop 0
	v_cndmask_b32_e32 v1, v1, v4, vcc
	v_add_u32_e32 v4, 1, v3
	v_mad_u64_u32 v[2:3], s[4:5], v2, v1, v[2:3]
	v_cmp_ne_u32_e32 vcc, v4, v2
	s_and_saveexec_b64 s[4:5], vcc
	s_xor_b64 s[4:5], exec, s[4:5]
	s_cbranch_execz .LBB0_528
	v_mov_b32_e32 v0, s20
	v_add_co_u32_e32 v2, vcc, 0x3000, v0
	v_mov_b32_e32 v0, s21
	s_nop 0
	v_addc_co_u32_e32 v3, vcc, 0, v0, vcc
	flat_load_dword v0, v[2:3] offset:1280 sc1
	s_add_u32 s24, s20, 0x3500
	s_addc_u32 s25, s21, 0
	s_waitcnt vmcnt(0) lgkmcnt(0)
	v_cmp_eq_u32_e32 vcc, v0, v1
	s_and_saveexec_b64 s[22:23], vcc
	s_cbranch_execz .LBB0_527
	s_mov_b32 s19, 1
	s_mov_b64 s[26:27], 0
	s_branch .LBB0_519

.LBB0_809:
	v_readlane_b32 s4, v255, 5
	s_lshl_b32 s4, s4, 2
	s_add_u32 s39, s16, s4
	s_addc_u32 s38, s17, 0
	v_mov_b32_e32 v1, s39
	v_add_co_u32_e32 v4, vcc, 0x1000, v1
	v_mov_b32_e32 v1, s38
	s_nop 0
	v_addc_co_u32_e32 v5, vcc, 0, v1, vcc
	flat_atomic_add v3, v[4:5], v230 offset:1024 sc0
	v_cvt_f32_u32_e32 v1, v2
	v_sub_u32_e32 v4, 0, v2
	v_rcp_iflag_f32_e32 v1, v1
	s_nop 0
	v_mul_f32_e32 v1, 0x4f7ffffe, v1
	v_cvt_u32_f32_e32 v1, v1
	v_mul_lo_u32 v4, v4, v1
	v_mul_hi_u32 v4, v1, v4
	v_add_u32_e32 v1, v1, v4
	s_waitcnt vmcnt(0) lgkmcnt(0)
	v_mul_hi_u32 v1, v3, v1
	v_mul_lo_u32 v4, v1, v2
	v_sub_u32_e32 v4, v3, v4
	v_cmp_ge_u32_e32 vcc, v4, v2
	v_add_u32_e32 v5, 1, v1
	s_nop 0
	v_cndmask_b32_e32 v1, v1, v5, vcc
	v_sub_u32_e32 v5, v4, v2
	v_cndmask_b32_e32 v4, v4, v5, vcc
	v_cmp_ge_u32_e32 vcc, v4, v2
	v_add_u32_e32 v4, 1, v1
	s_nop 0
	v_cndmask_b32_e32 v1, v1, v4, vcc
	v_add_u32_e32 v4, 1, v3
	v_mad_u64_u32 v[2:3], s[4:5], v2, v1, v[2:3]
	v_cmp_ne_u32_e32 vcc, v4, v2
	s_and_saveexec_b64 s[4:5], vcc
	s_xor_b64 s[4:5], exec, s[4:5]
	s_cbranch_execz .LBB0_822
	v_mov_b32_e32 v0, s16
	v_add_co_u32_e32 v2, vcc, 0x3000, v0
	v_mov_b32_e32 v0, s17
	s_nop 0
	v_addc_co_u32_e32 v3, vcc, 0, v0, vcc
	flat_load_dword v0, v[2:3] offset:1280 sc1
	s_add_u32 s20, s16, 0x3500
	s_addc_u32 s21, s17, 0
	s_waitcnt vmcnt(0) lgkmcnt(0)
	v_cmp_eq_u32_e32 vcc, v0, v1
	s_and_saveexec_b64 s[18:19], vcc
	s_cbranch_execz .LBB0_821
	s_mov_b32 s40, 1
	s_mov_b64 s[22:23], 0
	s_branch .LBB0_813
